# chunk_pre triangular-inverse block rewritten with an 11-deep rolling LDS prefetch window (row reads never exposed), same summation order
# baseline (speedup 1.0000x reference)
.LBB0_548:
	s_or_b64 exec, exec, s[42:43]
	s_waitcnt lgkmcnt(0)
	s_barrier
	ds_read_b128 v[0:3], v109 offset:23552
	v_add_u32_e32 v14, v101, v104
	ds_read_b128 v[4:7], v14 offset:28672
	s_waitcnt lgkmcnt(0)
	v_mfma_f32_16x16x32_bf16 v[4:7], v[0:3], v[4:7], 0
	s_nop 7
	v_cvt_pk_bf16_f32 v4, v4, s0
	v_cvt_pk_bf16_f32 v5, v5, s0
	v_cvt_pk_bf16_f32 v6, v6, s0
	v_cvt_pk_bf16_f32 v7, v7, s0
	ds_write_b16 v163, v4 offset:38912
	ds_write_b16 v163, v5 offset:38992
	ds_write_b16 v164, v6 offset:38912
	ds_write_b16 v151, v7 offset:38912
	ds_read_b128 v[4:7], v14 offset:29952
	s_waitcnt lgkmcnt(0)
	v_mfma_f32_16x16x32_bf16 v[4:7], v[0:3], v[4:7], 0
	s_nop 7
	v_cvt_pk_bf16_f32 v4, v4, s0
	v_cvt_pk_bf16_f32 v5, v5, s0
	v_cvt_pk_bf16_f32 v6, v6, s0
	v_cvt_pk_bf16_f32 v7, v7, s0
	ds_write_b16 v163, v4 offset:38944
	ds_write_b16 v163, v5 offset:39024
	ds_write_b16 v164, v6 offset:38944
	ds_write_b16 v151, v7 offset:38944
	s_and_saveexec_b64 s[42:43], s[72:73]
	s_cbranch_execz .LBB0_492
	ds_read_b128 v[206:209], v61 offset:54400
	ds_read_b128 v[210:213], v61 offset:54528
	ds_read_b128 v[214:217], v61 offset:54656
	ds_read_b128 v[220:223], v61 offset:54784
	ds_read_b128 v[224:227], v61 offset:54912
	ds_read_b128 v[228:231], v61 offset:54928
	ds_read_b128 v[232:235], v61 offset:55040
	ds_read_b128 v[236:239], v61 offset:55056
	ds_read_b128 v[4:7], v61 offset:55168
	ds_read_b128 v[8:11], v61 offset:55184
	ds_read_b128 v[16:19], v61 offset:55296
	ds_write_b16 v110, v112 offset:36352
	s_waitcnt lgkmcnt(11)
	v_fma_f32 v21, -v111, v206, v113
	ds_read_b128 v[206:209], v61 offset:55312
	v_cvt_pk_bf16_f32 v15, v21, s0
	ds_write_b16 v110, v15 offset:36432
	s_waitcnt lgkmcnt(12)
	v_fma_f32 v205, -v111, v210, v114
	v_fma_f32 v219, -v21, v211, 0
	ds_read_b128 v[210:213], v61 offset:55424
	v_add_f32_e32 v22, v205, v219
	v_cvt_pk_bf16_f32 v15, v22, s0
	ds_write_b16 v110, v15 offset:36512
	s_waitcnt lgkmcnt(13)
	v_fma_f32 v205, -v111, v214, v115
	v_fma_f32 v219, -v21, v215, 0
	v_fma_f32 v240, -v22, v216, 0
	ds_read_b128 v[214:217], v61 offset:55440
	v_add_f32_e32 v12, v205, v219
	v_add_f32_e32 v23, v240, v12
	v_cvt_pk_bf16_f32 v15, v23, s0
	ds_write_b16 v110, v15 offset:36592
	s_waitcnt lgkmcnt(14)
	v_fma_f32 v205, -v111, v220, v116
	v_fma_f32 v219, -v21, v221, 0
	v_fma_f32 v240, -v22, v222, 0
	v_fma_f32 v241, -v23, v223, 0
	ds_read_b128 v[220:223], v61 offset:55456
	v_add_f32_e32 v12, v205, v219
	v_add_f32_e32 v13, v240, v241
	v_add_f32_e32 v24, v13, v12
	v_cvt_pk_bf16_f32 v15, v24, s0
	ds_write_b16 v110, v15 offset:36672
	s_waitcnt lgkmcnt(15)
	v_fma_f32 v205, -v111, v224, v117
	v_fma_f32 v219, -v21, v225, 0
	v_fma_f32 v240, -v22, v226, 0
	v_fma_f32 v241, -v23, v227, 0
	ds_read_b128 v[224:227], v61 offset:55552
	s_waitcnt lgkmcnt(15)
	v_fma_f32 v205, -v24, v228, v205
	ds_read_b128 v[228:231], v61 offset:55568
	v_add_f32_e32 v13, v240, v241
	v_add_f32_e32 v12, v205, v219
	v_add_f32_e32 v25, v13, v12
	v_cvt_pk_bf16_f32 v15, v25, s0
	ds_write_b16 v110, v15 offset:36752
	s_waitcnt lgkmcnt(15)
	v_fma_f32 v205, -v111, v232, v118
	v_fma_f32 v219, -v21, v233, 0
	v_fma_f32 v240, -v22, v234, 0
	v_fma_f32 v241, -v23, v235, 0
	ds_read_b128 v[232:235], v61 offset:55584
	s_waitcnt lgkmcnt(15)
	v_fma_f32 v205, -v24, v236, v205
	v_fma_f32 v219, -v25, v237, v219
	ds_read_b128 v[236:239], v61 offset:55680
	v_add_f32_e32 v13, v240, v241
	v_add_f32_e32 v12, v205, v219
	v_add_f32_e32 v26, v13, v12
	v_cvt_pk_bf16_f32 v15, v26, s0
	ds_write_b16 v110, v15 offset:36832
	s_waitcnt lgkmcnt(15)
	v_fma_f32 v205, -v111, v4, v119
	v_fma_f32 v219, -v21, v5, 0
	v_fma_f32 v240, -v22, v6, 0
	v_fma_f32 v241, -v23, v7, 0
	ds_read_b128 v[4:7], v61 offset:55696
	s_waitcnt lgkmcnt(15)
	v_fma_f32 v205, -v24, v8, v205
	v_fma_f32 v219, -v25, v9, v219
	v_fma_f32 v240, -v26, v10, v240
	ds_read_b128 v[8:11], v61 offset:55712
	v_add_f32_e32 v12, v205, v219
	v_add_f32_e32 v13, v240, v241
	v_add_f32_e32 v27, v13, v12
	v_cvt_pk_bf16_f32 v15, v27, s0
	ds_write_b16 v110, v15 offset:36912
	s_waitcnt lgkmcnt(15)
	v_fma_f32 v205, -v111, v16, v120
	v_fma_f32 v219, -v21, v17, 0
	v_fma_f32 v240, -v22, v18, 0
	v_fma_f32 v241, -v23, v19, 0
	ds_read_b128 v[16:19], v61 offset:55808
	s_waitcnt lgkmcnt(15)
	v_fma_f32 v205, -v24, v206, v205
	v_fma_f32 v219, -v25, v207, v219
	v_fma_f32 v240, -v26, v208, v240
	v_fma_f32 v241, -v27, v209, v241
	ds_read_b128 v[206:209], v61 offset:55824
	v_add_f32_e32 v12, v205, v219
	v_add_f32_e32 v13, v240, v241
	v_add_f32_e32 v28, v13, v12
	v_cvt_pk_bf16_f32 v15, v28, s0
	ds_write_b16 v110, v15 offset:36992
	s_waitcnt lgkmcnt(15)
	v_fma_f32 v205, -v111, v210, v121
	v_fma_f32 v219, -v21, v211, 0
	v_fma_f32 v240, -v22, v212, 0
	v_fma_f32 v241, -v23, v213, 0
	ds_read_b128 v[210:213], v61 offset:55840
	s_waitcnt lgkmcnt(15)
	v_fma_f32 v205, -v24, v214, v205
	v_fma_f32 v219, -v25, v215, v219
	v_fma_f32 v240, -v26, v216, v240
	v_fma_f32 v241, -v27, v217, v241
	ds_read_b128 v[214:217], v61 offset:55936
	s_waitcnt lgkmcnt(15)
	v_fma_f32 v205, -v28, v220, v205
	ds_read_b128 v[220:223], v61 offset:55952
	v_add_f32_e32 v13, v240, v241
	v_add_f32_e32 v12, v205, v219
	v_add_f32_e32 v29, v13, v12
	v_cvt_pk_bf16_f32 v15, v29, s0
	ds_write_b16 v110, v15 offset:37072
	s_waitcnt lgkmcnt(15)
	v_fma_f32 v205, -v111, v224, v122
	v_fma_f32 v219, -v21, v225, 0
	v_fma_f32 v240, -v22, v226, 0
	v_fma_f32 v241, -v23, v227, 0
	ds_read_b128 v[224:227], v61 offset:55968
	s_waitcnt lgkmcnt(15)
	v_fma_f32 v205, -v24, v228, v205
	v_fma_f32 v219, -v25, v229, v219
	v_fma_f32 v240, -v26, v230, v240
	v_fma_f32 v241, -v27, v231, v241
	ds_read_b128 v[228:231], v61 offset:55984
	s_waitcnt lgkmcnt(14)
	v_fma_f32 v205, -v28, v232, v205
	v_fma_f32 v219, -v29, v233, v219
	ds_read_b128 v[232:235], v61 offset:56064
	v_add_f32_e32 v13, v240, v241
	v_add_f32_e32 v12, v205, v219
	v_add_f32_e32 v30, v13, v12
	v_cvt_pk_bf16_f32 v15, v30, s0
	ds_write_b16 v110, v15 offset:37152
	s_waitcnt lgkmcnt(15)
	v_fma_f32 v205, -v111, v236, v123
	v_fma_f32 v219, -v21, v237, 0
	v_fma_f32 v240, -v22, v238, 0
	v_fma_f32 v241, -v23, v239, 0
	ds_read_b128 v[236:239], v61 offset:56080
	s_waitcnt lgkmcnt(14)
	v_fma_f32 v205, -v24, v4, v205
	v_fma_f32 v219, -v25, v5, v219
	v_fma_f32 v240, -v26, v6, v240
	v_fma_f32 v241, -v27, v7, v241
	ds_read_b128 v[4:7], v61 offset:56096
	s_waitcnt lgkmcnt(14)
	v_fma_f32 v205, -v28, v8, v205
	v_fma_f32 v219, -v29, v9, v219
	v_fma_f32 v240, -v30, v10, v240
	ds_read_b128 v[8:11], v61 offset:56112
	v_add_f32_e32 v12, v205, v219
	v_add_f32_e32 v13, v240, v241
	v_add_f32_e32 v31, v13, v12
	v_cvt_pk_bf16_f32 v15, v31, s0
	ds_write_b16 v110, v15 offset:37232
	s_waitcnt lgkmcnt(14)
	v_fma_f32 v205, -v111, v16, v124
	v_fma_f32 v219, -v21, v17, 0
	v_fma_f32 v240, -v22, v18, 0
	v_fma_f32 v241, -v23, v19, 0
	ds_read_b128 v[16:19], v61 offset:56192
	s_waitcnt lgkmcnt(14)
	v_fma_f32 v205, -v24, v206, v205
	v_fma_f32 v219, -v25, v207, v219
	v_fma_f32 v240, -v26, v208, v240
	v_fma_f32 v241, -v27, v209, v241
	ds_read_b128 v[206:209], v61 offset:56208
	s_waitcnt lgkmcnt(13)
	v_fma_f32 v205, -v28, v210, v205
	v_fma_f32 v219, -v29, v211, v219
	v_fma_f32 v240, -v30, v212, v240
	v_fma_f32 v241, -v31, v213, v241
	ds_read_b128 v[210:213], v61 offset:56224
	v_add_f32_e32 v12, v205, v219
	v_add_f32_e32 v13, v240, v241
	v_add_f32_e32 v32, v13, v12
	v_cvt_pk_bf16_f32 v15, v32, s0
	ds_write_b16 v110, v15 offset:37312
	s_waitcnt lgkmcnt(14)
	v_fma_f32 v205, -v111, v214, v125
	v_fma_f32 v219, -v21, v215, 0
	v_fma_f32 v240, -v22, v216, 0
	v_fma_f32 v241, -v23, v217, 0
	ds_read_b128 v[214:217], v61 offset:56240
	s_waitcnt lgkmcnt(14)
	v_fma_f32 v205, -v24, v220, v205
	v_fma_f32 v219, -v25, v221, v219
	v_fma_f32 v240, -v26, v222, v240
	v_fma_f32 v241, -v27, v223, v241
	ds_read_b128 v[220:223], v61 offset:56320
	s_waitcnt lgkmcnt(13)
	v_fma_f32 v205, -v28, v224, v205
	v_fma_f32 v219, -v29, v225, v219
	v_fma_f32 v240, -v30, v226, v240
	v_fma_f32 v241, -v31, v227, v241
	ds_read_b128 v[224:227], v61 offset:56336
	s_waitcnt lgkmcnt(13)
	v_fma_f32 v205, -v32, v228, v205
	ds_read_b128 v[228:231], v61 offset:56352
	v_add_f32_e32 v13, v240, v241
	v_add_f32_e32 v12, v205, v219
	v_add_f32_e32 v33, v13, v12
	v_cvt_pk_bf16_f32 v15, v33, s0
	ds_write_b16 v110, v15 offset:37392
	s_waitcnt lgkmcnt(14)
	v_fma_f32 v205, -v111, v232, v126
	v_fma_f32 v219, -v21, v233, 0
	v_fma_f32 v240, -v22, v234, 0
	v_fma_f32 v241, -v23, v235, 0
	ds_read_b128 v[232:235], v61 offset:56368
	s_waitcnt lgkmcnt(13)
	v_fma_f32 v205, -v24, v236, v205
	v_fma_f32 v219, -v25, v237, v219
	v_fma_f32 v240, -v26, v238, v240
	v_fma_f32 v241, -v27, v239, v241
	ds_read_b128 v[236:239], v61 offset:56448
	s_waitcnt lgkmcnt(13)
	v_fma_f32 v205, -v28, v4, v205
	v_fma_f32 v219, -v29, v5, v219
	v_fma_f32 v240, -v30, v6, v240
	v_fma_f32 v241, -v31, v7, v241
	ds_read_b128 v[4:7], v61 offset:56464
	s_waitcnt lgkmcnt(13)
	v_fma_f32 v205, -v32, v8, v205
	v_fma_f32 v219, -v33, v9, v219
	ds_read_b128 v[8:11], v61 offset:56480
	v_add_f32_e32 v13, v240, v241
	v_add_f32_e32 v12, v205, v219
	v_add_f32_e32 v34, v13, v12
	v_cvt_pk_bf16_f32 v15, v34, s0
	ds_write_b16 v110, v15 offset:37472
	s_waitcnt lgkmcnt(13)
	v_fma_f32 v205, -v111, v16, v127
	v_fma_f32 v219, -v21, v17, 0
	v_fma_f32 v240, -v22, v18, 0
	v_fma_f32 v241, -v23, v19, 0
	ds_read_b128 v[16:19], v61 offset:56496
	s_waitcnt lgkmcnt(13)
	v_fma_f32 v205, -v24, v206, v205
	v_fma_f32 v219, -v25, v207, v219
	v_fma_f32 v240, -v26, v208, v240
	v_fma_f32 v241, -v27, v209, v241
	ds_read_b128 v[206:209], v61 offset:56512
	s_waitcnt lgkmcnt(13)
	v_fma_f32 v205, -v28, v210, v205
	v_fma_f32 v219, -v29, v211, v219
	v_fma_f32 v240, -v30, v212, v240
	v_fma_f32 v241, -v31, v213, v241
	ds_read_b128 v[210:213], v61 offset:56576
	s_waitcnt lgkmcnt(12)
	v_fma_f32 v205, -v32, v214, v205
	v_fma_f32 v219, -v33, v215, v219
	v_fma_f32 v240, -v34, v216, v240
	ds_read_b128 v[214:217], v61 offset:56592
	v_add_f32_e32 v12, v205, v219
	v_add_f32_e32 v13, v240, v241
	v_add_f32_e32 v35, v13, v12
	v_cvt_pk_bf16_f32 v15, v35, s0
	ds_write_b16 v110, v15 offset:37552
	s_waitcnt lgkmcnt(13)
	v_fma_f32 v205, -v111, v220, v128
	v_fma_f32 v219, -v21, v221, 0
	v_fma_f32 v240, -v22, v222, 0
	v_fma_f32 v241, -v23, v223, 0
	ds_read_b128 v[220:223], v61 offset:56608
	s_waitcnt lgkmcnt(13)
	v_fma_f32 v205, -v24, v224, v205
	v_fma_f32 v219, -v25, v225, v219
	v_fma_f32 v240, -v26, v226, v240
	v_fma_f32 v241, -v27, v227, v241
	ds_read_b128 v[224:227], v61 offset:56624
	s_waitcnt lgkmcnt(13)
	v_fma_f32 v205, -v28, v228, v205
	v_fma_f32 v219, -v29, v229, v219
	v_fma_f32 v240, -v30, v230, v240
	v_fma_f32 v241, -v31, v231, v241
	ds_read_b128 v[228:231], v61 offset:56640
	s_waitcnt lgkmcnt(12)
	v_fma_f32 v205, -v32, v232, v205
	v_fma_f32 v219, -v33, v233, v219
	v_fma_f32 v240, -v34, v234, v240
	v_fma_f32 v241, -v35, v235, v241
	ds_read_b128 v[232:235], v61 offset:56704
	v_add_f32_e32 v12, v205, v219
	v_add_f32_e32 v13, v240, v241
	v_add_f32_e32 v36, v13, v12
	v_cvt_pk_bf16_f32 v15, v36, s0
	ds_write_b16 v110, v15 offset:37632
	s_waitcnt lgkmcnt(13)
	v_fma_f32 v205, -v111, v236, v129
	v_fma_f32 v219, -v21, v237, 0
	v_fma_f32 v240, -v22, v238, 0
	v_fma_f32 v241, -v23, v239, 0
	ds_read_b128 v[236:239], v61 offset:56720
	s_waitcnt lgkmcnt(13)
	v_fma_f32 v205, -v24, v4, v205
	v_fma_f32 v219, -v25, v5, v219
	v_fma_f32 v240, -v26, v6, v240
	v_fma_f32 v241, -v27, v7, v241
	ds_read_b128 v[4:7], v61 offset:56736
	s_waitcnt lgkmcnt(13)
	v_fma_f32 v205, -v28, v8, v205
	v_fma_f32 v219, -v29, v9, v219
	v_fma_f32 v240, -v30, v10, v240
	v_fma_f32 v241, -v31, v11, v241
	ds_read_b128 v[8:11], v61 offset:56752
	s_waitcnt lgkmcnt(12)
	v_fma_f32 v205, -v32, v16, v205
	v_fma_f32 v219, -v33, v17, v219
	v_fma_f32 v240, -v34, v18, v240
	v_fma_f32 v241, -v35, v19, v241
	ds_read_b128 v[16:19], v61 offset:56768
	s_waitcnt lgkmcnt(12)
	v_fma_f32 v205, -v36, v206, v205
	ds_read_b128 v[206:209], v61 offset:56832
	v_add_f32_e32 v13, v240, v241
	v_add_f32_e32 v12, v205, v219
	v_add_f32_e32 v37, v13, v12
	v_cvt_pk_bf16_f32 v15, v37, s0
	ds_write_b16 v110, v15 offset:37712
	s_waitcnt lgkmcnt(13)
	v_fma_f32 v205, -v111, v210, v130
	v_fma_f32 v219, -v21, v211, 0
	v_fma_f32 v240, -v22, v212, 0
	v_fma_f32 v241, -v23, v213, 0
	ds_read_b128 v[210:213], v61 offset:56848
	s_waitcnt lgkmcnt(13)
	v_fma_f32 v205, -v24, v214, v205
	v_fma_f32 v219, -v25, v215, v219
	v_fma_f32 v240, -v26, v216, v240
	v_fma_f32 v241, -v27, v217, v241
	ds_read_b128 v[214:217], v61 offset:56864
	s_waitcnt lgkmcnt(12)
	v_fma_f32 v205, -v28, v220, v205
	v_fma_f32 v219, -v29, v221, v219
	v_fma_f32 v240, -v30, v222, v240
	v_fma_f32 v241, -v31, v223, v241
	ds_read_b128 v[220:223], v61 offset:56880
	s_waitcnt lgkmcnt(12)
	v_fma_f32 v205, -v32, v224, v205
	v_fma_f32 v219, -v33, v225, v219
	v_fma_f32 v240, -v34, v226, v240
	v_fma_f32 v241, -v35, v227, v241
	ds_read_b128 v[224:227], v61 offset:56896
	s_waitcnt lgkmcnt(12)
	v_fma_f32 v205, -v36, v228, v205
	v_fma_f32 v219, -v37, v229, v219
	ds_read_b128 v[228:231], v61 offset:56960
	v_add_f32_e32 v13, v240, v241
	v_add_f32_e32 v12, v205, v219
	v_add_f32_e32 v38, v13, v12
	v_cvt_pk_bf16_f32 v15, v38, s0
	ds_write_b16 v110, v15 offset:37792
	s_waitcnt lgkmcnt(13)
	v_fma_f32 v205, -v111, v232, v131
	v_fma_f32 v219, -v21, v233, 0
	v_fma_f32 v240, -v22, v234, 0
	v_fma_f32 v241, -v23, v235, 0
	ds_read_b128 v[232:235], v61 offset:56976
	s_waitcnt lgkmcnt(12)
	v_fma_f32 v205, -v24, v236, v205
	v_fma_f32 v219, -v25, v237, v219
	v_fma_f32 v240, -v26, v238, v240
	v_fma_f32 v241, -v27, v239, v241
	ds_read_b128 v[236:239], v61 offset:56992
	s_waitcnt lgkmcnt(12)
	v_fma_f32 v205, -v28, v4, v205
	v_fma_f32 v219, -v29, v5, v219
	v_fma_f32 v240, -v30, v6, v240
	v_fma_f32 v241, -v31, v7, v241
	ds_read_b128 v[4:7], v61 offset:57008
	s_waitcnt lgkmcnt(12)
	v_fma_f32 v205, -v32, v8, v205
	v_fma_f32 v219, -v33, v9, v219
	v_fma_f32 v240, -v34, v10, v240
	v_fma_f32 v241, -v35, v11, v241
	ds_read_b128 v[8:11], v61 offset:57024
	s_waitcnt lgkmcnt(12)
	v_fma_f32 v205, -v36, v16, v205
	v_fma_f32 v219, -v37, v17, v219
	v_fma_f32 v240, -v38, v18, v240
	ds_read_b128 v[16:19], v61 offset:57040
	v_add_f32_e32 v12, v205, v219
	v_add_f32_e32 v13, v240, v241
	v_add_f32_e32 v39, v13, v12
	v_cvt_pk_bf16_f32 v15, v39, s0
	ds_write_b16 v110, v15 offset:37872
	s_waitcnt lgkmcnt(13)
	v_fma_f32 v205, -v111, v206, v132
	v_fma_f32 v219, -v21, v207, 0
	v_fma_f32 v240, -v22, v208, 0
	v_fma_f32 v241, -v23, v209, 0
	ds_read_b128 v[206:209], v61 offset:57088
	s_waitcnt lgkmcnt(12)
	v_fma_f32 v205, -v24, v210, v205
	v_fma_f32 v219, -v25, v211, v219
	v_fma_f32 v240, -v26, v212, v240
	v_fma_f32 v241, -v27, v213, v241
	ds_read_b128 v[210:213], v61 offset:57104
	s_waitcnt lgkmcnt(12)
	v_fma_f32 v205, -v28, v214, v205
	v_fma_f32 v219, -v29, v215, v219
	v_fma_f32 v240, -v30, v216, v240
	v_fma_f32 v241, -v31, v217, v241
	ds_read_b128 v[214:217], v61 offset:57120
	s_waitcnt lgkmcnt(12)
	v_fma_f32 v205, -v32, v220, v205
	v_fma_f32 v219, -v33, v221, v219
	v_fma_f32 v240, -v34, v222, v240
	v_fma_f32 v241, -v35, v223, v241
	ds_read_b128 v[220:223], v61 offset:57136
	s_waitcnt lgkmcnt(12)
	v_fma_f32 v205, -v36, v224, v205
	v_fma_f32 v219, -v37, v225, v219
	v_fma_f32 v240, -v38, v226, v240
	v_fma_f32 v241, -v39, v227, v241
	ds_read_b128 v[224:227], v61 offset:57152
	v_add_f32_e32 v12, v205, v219
	v_add_f32_e32 v13, v240, v241
	v_add_f32_e32 v40, v13, v12
	v_cvt_pk_bf16_f32 v15, v40, s0
	ds_write_b16 v110, v15 offset:37952
	s_waitcnt lgkmcnt(13)
	v_fma_f32 v205, -v111, v228, v133
	v_fma_f32 v219, -v21, v229, 0
	v_fma_f32 v240, -v22, v230, 0
	v_fma_f32 v241, -v23, v231, 0
	ds_read_b128 v[228:231], v61 offset:57168
	s_waitcnt lgkmcnt(12)
	v_fma_f32 v205, -v24, v232, v205
	v_fma_f32 v219, -v25, v233, v219
	v_fma_f32 v240, -v26, v234, v240
	v_fma_f32 v241, -v27, v235, v241
	ds_read_b128 v[232:235], v61 offset:57216
	s_waitcnt lgkmcnt(12)
	v_fma_f32 v205, -v28, v236, v205
	v_fma_f32 v219, -v29, v237, v219
	v_fma_f32 v240, -v30, v238, v240
	v_fma_f32 v241, -v31, v239, v241
	ds_read_b128 v[236:239], v61 offset:57232
	s_waitcnt lgkmcnt(12)
	v_fma_f32 v205, -v32, v4, v205
	v_fma_f32 v219, -v33, v5, v219
	v_fma_f32 v240, -v34, v6, v240
	v_fma_f32 v241, -v35, v7, v241
	ds_read_b128 v[4:7], v61 offset:57248
	s_waitcnt lgkmcnt(12)
	v_fma_f32 v205, -v36, v8, v205
	v_fma_f32 v219, -v37, v9, v219
	v_fma_f32 v240, -v38, v10, v240
	v_fma_f32 v241, -v39, v11, v241
	ds_read_b128 v[8:11], v61 offset:57264
	s_waitcnt lgkmcnt(12)
	v_fma_f32 v205, -v40, v16, v205
	ds_read_b128 v[16:19], v61 offset:57280
	v_add_f32_e32 v13, v240, v241
	v_add_f32_e32 v12, v205, v219
	v_add_f32_e32 v41, v13, v12
	v_cvt_pk_bf16_f32 v15, v41, s0
	ds_write_b16 v110, v15 offset:38032
	s_waitcnt lgkmcnt(12)
	v_fma_f32 v205, -v111, v206, v134
	v_fma_f32 v219, -v21, v207, 0
	v_fma_f32 v240, -v22, v208, 0
	v_fma_f32 v241, -v23, v209, 0
	ds_read_b128 v[206:209], v61 offset:57296
	s_waitcnt lgkmcnt(12)
	v_fma_f32 v205, -v24, v210, v205
	v_fma_f32 v219, -v25, v211, v219
	v_fma_f32 v240, -v26, v212, v240
	v_fma_f32 v241, -v27, v213, v241
	ds_read_b128 v[210:213], v61 offset:57344
	s_waitcnt lgkmcnt(12)
	v_fma_f32 v205, -v28, v214, v205
	v_fma_f32 v219, -v29, v215, v219
	v_fma_f32 v240, -v30, v216, v240
	v_fma_f32 v241, -v31, v217, v241
	ds_read_b128 v[214:217], v61 offset:57360
	s_waitcnt lgkmcnt(12)
	v_fma_f32 v205, -v32, v220, v205
	v_fma_f32 v219, -v33, v221, v219
	v_fma_f32 v240, -v34, v222, v240
	v_fma_f32 v241, -v35, v223, v241
	ds_read_b128 v[220:223], v61 offset:57376
	s_waitcnt lgkmcnt(12)
	v_fma_f32 v205, -v36, v224, v205
	v_fma_f32 v219, -v37, v225, v219
	v_fma_f32 v240, -v38, v226, v240
	v_fma_f32 v241, -v39, v227, v241
	ds_read_b128 v[224:227], v61 offset:57392
	s_waitcnt lgkmcnt(11)
	v_fma_f32 v205, -v40, v228, v205
	v_fma_f32 v219, -v41, v229, v219
	ds_read_b128 v[228:231], v61 offset:57408
	v_add_f32_e32 v13, v240, v241
	v_add_f32_e32 v12, v205, v219
	v_add_f32_e32 v42, v13, v12
	v_cvt_pk_bf16_f32 v15, v42, s0
	ds_write_b16 v110, v15 offset:38112
	s_waitcnt lgkmcnt(12)
	v_fma_f32 v205, -v111, v232, v135
	v_fma_f32 v219, -v21, v233, 0
	v_fma_f32 v240, -v22, v234, 0
	v_fma_f32 v241, -v23, v235, 0
	ds_read_b128 v[232:235], v61 offset:57424
	s_waitcnt lgkmcnt(12)
	v_fma_f32 v205, -v24, v236, v205
	v_fma_f32 v219, -v25, v237, v219
	v_fma_f32 v240, -v26, v238, v240
	v_fma_f32 v241, -v27, v239, v241
	ds_read_b128 v[236:239], v61 offset:57472
	s_waitcnt lgkmcnt(12)
	v_fma_f32 v205, -v28, v4, v205
	v_fma_f32 v219, -v29, v5, v219
	v_fma_f32 v240, -v30, v6, v240
	v_fma_f32 v241, -v31, v7, v241
	ds_read_b128 v[4:7], v61 offset:57488
	s_waitcnt lgkmcnt(12)
	v_fma_f32 v205, -v32, v8, v205
	v_fma_f32 v219, -v33, v9, v219
	v_fma_f32 v240, -v34, v10, v240
	v_fma_f32 v241, -v35, v11, v241
	ds_read_b128 v[8:11], v61 offset:57504
	s_waitcnt lgkmcnt(12)
	v_fma_f32 v205, -v36, v16, v205
	v_fma_f32 v219, -v37, v17, v219
	v_fma_f32 v240, -v38, v18, v240
	v_fma_f32 v241, -v39, v19, v241
	ds_read_b128 v[16:19], v61 offset:57520
	s_waitcnt lgkmcnt(11)
	v_fma_f32 v205, -v40, v206, v205
	v_fma_f32 v219, -v41, v207, v219
	v_fma_f32 v240, -v42, v208, v240
	ds_read_b128 v[206:209], v61 offset:57536
	v_add_f32_e32 v12, v205, v219
	v_add_f32_e32 v13, v240, v241
	v_add_f32_e32 v43, v13, v12
	v_cvt_pk_bf16_f32 v15, v43, s0
	ds_write_b16 v110, v15 offset:38192
	s_waitcnt lgkmcnt(12)
	v_fma_f32 v205, -v111, v210, v136
	v_fma_f32 v219, -v21, v211, 0
	v_fma_f32 v240, -v22, v212, 0
	v_fma_f32 v241, -v23, v213, 0
	ds_read_b128 v[210:213], v61 offset:57552
	s_waitcnt lgkmcnt(12)
	v_fma_f32 v205, -v24, v214, v205
	v_fma_f32 v219, -v25, v215, v219
	v_fma_f32 v240, -v26, v216, v240
	v_fma_f32 v241, -v27, v217, v241
	ds_read_b128 v[214:217], v61 offset:57568
	s_waitcnt lgkmcnt(12)
	v_fma_f32 v205, -v28, v220, v205
	v_fma_f32 v219, -v29, v221, v219
	v_fma_f32 v240, -v30, v222, v240
	v_fma_f32 v241, -v31, v223, v241
	ds_read_b128 v[220:223], v61 offset:57600
	s_waitcnt lgkmcnt(12)
	v_fma_f32 v205, -v32, v224, v205
	v_fma_f32 v219, -v33, v225, v219
	v_fma_f32 v240, -v34, v226, v240
	v_fma_f32 v241, -v35, v227, v241
	ds_read_b128 v[224:227], v61 offset:57616
	s_waitcnt lgkmcnt(12)
	v_fma_f32 v205, -v36, v228, v205
	v_fma_f32 v219, -v37, v229, v219
	v_fma_f32 v240, -v38, v230, v240
	v_fma_f32 v241, -v39, v231, v241
	ds_read_b128 v[228:231], v61 offset:57632
	s_waitcnt lgkmcnt(11)
	v_fma_f32 v205, -v40, v232, v205
	v_fma_f32 v219, -v41, v233, v219
	v_fma_f32 v240, -v42, v234, v240
	v_fma_f32 v241, -v43, v235, v241
	ds_read_b128 v[232:235], v61 offset:57648
	v_add_f32_e32 v12, v205, v219
	v_add_f32_e32 v13, v240, v241
	v_add_f32_e32 v44, v13, v12
	v_cvt_pk_bf16_f32 v15, v44, s0
	ds_write_b16 v110, v15 offset:38272
	s_waitcnt lgkmcnt(12)
	v_fma_f32 v205, -v111, v236, v137
	v_fma_f32 v219, -v21, v237, 0
	v_fma_f32 v240, -v22, v238, 0
	v_fma_f32 v241, -v23, v239, 0
	ds_read_b128 v[236:239], v61 offset:57664
	s_waitcnt lgkmcnt(12)
	v_fma_f32 v205, -v24, v4, v205
	v_fma_f32 v219, -v25, v5, v219
	v_fma_f32 v240, -v26, v6, v240
	v_fma_f32 v241, -v27, v7, v241
	ds_read_b128 v[4:7], v61 offset:57680
	s_waitcnt lgkmcnt(12)
	v_fma_f32 v205, -v28, v8, v205
	v_fma_f32 v219, -v29, v9, v219
	v_fma_f32 v240, -v30, v10, v240
	v_fma_f32 v241, -v31, v11, v241
	ds_read_b128 v[8:11], v61 offset:57696
	s_waitcnt lgkmcnt(12)
	v_fma_f32 v205, -v32, v16, v205
	v_fma_f32 v219, -v33, v17, v219
	v_fma_f32 v240, -v34, v18, v240
	v_fma_f32 v241, -v35, v19, v241
	ds_read_b128 v[16:19], v61 offset:57728
	s_waitcnt lgkmcnt(12)
	v_fma_f32 v205, -v36, v206, v205
	v_fma_f32 v219, -v37, v207, v219
	v_fma_f32 v240, -v38, v208, v240
	v_fma_f32 v241, -v39, v209, v241
	ds_read_b128 v[206:209], v61 offset:57744
	s_waitcnt lgkmcnt(11)
	v_fma_f32 v205, -v40, v210, v205
	v_fma_f32 v219, -v41, v211, v219
	v_fma_f32 v240, -v42, v212, v240
	v_fma_f32 v241, -v43, v213, v241
	ds_read_b128 v[210:213], v61 offset:57760
	s_waitcnt lgkmcnt(11)
	v_fma_f32 v205, -v44, v214, v205
	ds_read_b128 v[214:217], v61 offset:57776
	v_add_f32_e32 v13, v240, v241
	v_add_f32_e32 v12, v205, v219
	v_add_f32_e32 v45, v13, v12
	v_cvt_pk_bf16_f32 v15, v45, s0
	ds_write_b16 v110, v15 offset:38352
	s_waitcnt lgkmcnt(12)
	v_fma_f32 v205, -v111, v220, v138
	v_fma_f32 v219, -v21, v221, 0
	v_fma_f32 v240, -v22, v222, 0
	v_fma_f32 v241, -v23, v223, 0
	ds_read_b128 v[220:223], v61 offset:57792
	s_waitcnt lgkmcnt(12)
	v_fma_f32 v205, -v24, v224, v205
	v_fma_f32 v219, -v25, v225, v219
	v_fma_f32 v240, -v26, v226, v240
	v_fma_f32 v241, -v27, v227, v241
	ds_read_b128 v[224:227], v61 offset:57808
	s_waitcnt lgkmcnt(12)
	v_fma_f32 v205, -v28, v228, v205
	v_fma_f32 v219, -v29, v229, v219
	v_fma_f32 v240, -v30, v230, v240
	v_fma_f32 v241, -v31, v231, v241
	ds_read_b128 v[228:231], v61 offset:57824
	s_waitcnt lgkmcnt(12)
	v_fma_f32 v205, -v32, v232, v205
	v_fma_f32 v219, -v33, v233, v219
	v_fma_f32 v240, -v34, v234, v240
	v_fma_f32 v241, -v35, v235, v241
	ds_read_b128 v[232:235], v61 offset:57856
	s_waitcnt lgkmcnt(11)
	v_fma_f32 v205, -v36, v236, v205
	v_fma_f32 v219, -v37, v237, v219
	v_fma_f32 v240, -v38, v238, v240
	v_fma_f32 v241, -v39, v239, v241
	ds_read_b128 v[236:239], v61 offset:57872
	s_waitcnt lgkmcnt(11)
	v_fma_f32 v205, -v40, v4, v205
	v_fma_f32 v219, -v41, v5, v219
	v_fma_f32 v240, -v42, v6, v240
	v_fma_f32 v241, -v43, v7, v241
	ds_read_b128 v[4:7], v61 offset:57888
	s_waitcnt lgkmcnt(11)
	v_fma_f32 v205, -v44, v8, v205
	v_fma_f32 v219, -v45, v9, v219
	ds_read_b128 v[8:11], v61 offset:57904
	v_add_f32_e32 v13, v240, v241
	v_add_f32_e32 v12, v205, v219
	v_add_f32_e32 v46, v13, v12
	v_cvt_pk_bf16_f32 v15, v46, s0
	ds_write_b16 v110, v15 offset:38432
	s_waitcnt lgkmcnt(12)
	v_fma_f32 v205, -v111, v16, v139
	v_fma_f32 v219, -v21, v17, 0
	v_fma_f32 v240, -v22, v18, 0
	v_fma_f32 v241, -v23, v19, 0
	ds_read_b128 v[16:19], v61 offset:57920
	s_waitcnt lgkmcnt(12)
	v_fma_f32 v205, -v24, v206, v205
	v_fma_f32 v219, -v25, v207, v219
	v_fma_f32 v240, -v26, v208, v240
	v_fma_f32 v241, -v27, v209, v241
	ds_read_b128 v[206:209], v61 offset:57936
	s_waitcnt lgkmcnt(12)
	v_fma_f32 v205, -v28, v210, v205
	v_fma_f32 v219, -v29, v211, v219
	v_fma_f32 v240, -v30, v212, v240
	v_fma_f32 v241, -v31, v213, v241
	ds_read_b128 v[210:213], v61 offset:57952
	s_waitcnt lgkmcnt(12)
	v_fma_f32 v205, -v32, v214, v205
	v_fma_f32 v219, -v33, v215, v219
	v_fma_f32 v240, -v34, v216, v240
	v_fma_f32 v241, -v35, v217, v241
	ds_read_b128 v[214:217], v61 offset:57984
	s_waitcnt lgkmcnt(11)
	v_fma_f32 v205, -v36, v220, v205
	v_fma_f32 v219, -v37, v221, v219
	v_fma_f32 v240, -v38, v222, v240
	v_fma_f32 v241, -v39, v223, v241
	ds_read_b128 v[220:223], v61 offset:58000
	s_waitcnt lgkmcnt(11)
	v_fma_f32 v205, -v40, v224, v205
	v_fma_f32 v219, -v41, v225, v219
	v_fma_f32 v240, -v42, v226, v240
	v_fma_f32 v241, -v43, v227, v241
	ds_read_b128 v[224:227], v61 offset:58016
	s_waitcnt lgkmcnt(11)
	v_fma_f32 v205, -v44, v228, v205
	v_fma_f32 v219, -v45, v229, v219
	v_fma_f32 v240, -v46, v230, v240
	ds_read_b128 v[228:231], v61 offset:58032
	v_add_f32_e32 v12, v205, v219
	v_add_f32_e32 v13, v240, v241
	v_add_f32_e32 v47, v13, v12
	v_cvt_pk_bf16_f32 v15, v47, s0
	ds_write_b16 v110, v15 offset:38512
	s_waitcnt lgkmcnt(12)
	v_fma_f32 v205, -v111, v232, v140
	v_fma_f32 v219, -v21, v233, 0
	v_fma_f32 v240, -v22, v234, 0
	v_fma_f32 v241, -v23, v235, 0
	ds_read_b128 v[232:235], v61 offset:58048
	s_waitcnt lgkmcnt(12)
	v_fma_f32 v205, -v24, v236, v205
	v_fma_f32 v219, -v25, v237, v219
	v_fma_f32 v240, -v26, v238, v240
	v_fma_f32 v241, -v27, v239, v241
	ds_read_b128 v[236:239], v61 offset:58064
	s_waitcnt lgkmcnt(12)
	v_fma_f32 v205, -v28, v4, v205
	v_fma_f32 v219, -v29, v5, v219
	v_fma_f32 v240, -v30, v6, v240
	v_fma_f32 v241, -v31, v7, v241
	ds_read_b128 v[4:7], v61 offset:58080
	s_waitcnt lgkmcnt(12)
	v_fma_f32 v205, -v32, v8, v205
	v_fma_f32 v219, -v33, v9, v219
	v_fma_f32 v240, -v34, v10, v240
	v_fma_f32 v241, -v35, v11, v241
	ds_read_b128 v[8:11], v61 offset:58096
	s_waitcnt lgkmcnt(11)
	v_fma_f32 v205, -v36, v16, v205
	v_fma_f32 v219, -v37, v17, v219
	v_fma_f32 v240, -v38, v18, v240
	v_fma_f32 v241, -v39, v19, v241
	ds_read_b128 v[16:19], v61 offset:58112
	s_waitcnt lgkmcnt(11)
	v_fma_f32 v205, -v40, v206, v205
	v_fma_f32 v219, -v41, v207, v219
	v_fma_f32 v240, -v42, v208, v240
	v_fma_f32 v241, -v43, v209, v241
	ds_read_b128 v[206:209], v61 offset:58128
	s_waitcnt lgkmcnt(11)
	v_fma_f32 v205, -v44, v210, v205
	v_fma_f32 v219, -v45, v211, v219
	v_fma_f32 v240, -v46, v212, v240
	v_fma_f32 v241, -v47, v213, v241
	ds_read_b128 v[210:213], v61 offset:58144
	v_add_f32_e32 v12, v205, v219
	v_add_f32_e32 v13, v240, v241
	v_add_f32_e32 v48, v13, v12
	v_cvt_pk_bf16_f32 v15, v48, s0
	ds_write_b16 v110, v15 offset:38592
	s_waitcnt lgkmcnt(12)
	v_fma_f32 v205, -v111, v214, v141
	v_fma_f32 v219, -v21, v215, 0
	v_fma_f32 v240, -v22, v216, 0
	v_fma_f32 v241, -v23, v217, 0
	ds_read_b128 v[214:217], v61 offset:58160
	s_waitcnt lgkmcnt(12)
	v_fma_f32 v205, -v24, v220, v205
	v_fma_f32 v219, -v25, v221, v219
	v_fma_f32 v240, -v26, v222, v240
	v_fma_f32 v241, -v27, v223, v241
	ds_read_b128 v[220:223], v61 offset:58176
	s_waitcnt lgkmcnt(12)
	v_fma_f32 v205, -v28, v224, v205
	v_fma_f32 v219, -v29, v225, v219
	v_fma_f32 v240, -v30, v226, v240
	v_fma_f32 v241, -v31, v227, v241
	ds_read_b128 v[224:227], v61 offset:58192
	s_waitcnt lgkmcnt(12)
	v_fma_f32 v205, -v32, v228, v205
	v_fma_f32 v219, -v33, v229, v219
	v_fma_f32 v240, -v34, v230, v240
	v_fma_f32 v241, -v35, v231, v241
	ds_read_b128 v[228:231], v61 offset:58208
	s_waitcnt lgkmcnt(11)
	v_fma_f32 v205, -v36, v232, v205
	v_fma_f32 v219, -v37, v233, v219
	v_fma_f32 v240, -v38, v234, v240
	v_fma_f32 v241, -v39, v235, v241
	ds_read_b128 v[232:235], v61 offset:58224
	s_waitcnt lgkmcnt(11)
	v_fma_f32 v205, -v40, v236, v205
	v_fma_f32 v219, -v41, v237, v219
	v_fma_f32 v240, -v42, v238, v240
	v_fma_f32 v241, -v43, v239, v241
	ds_read_b128 v[236:239], v61 offset:58240
	s_waitcnt lgkmcnt(11)
	v_fma_f32 v205, -v44, v4, v205
	v_fma_f32 v219, -v45, v5, v219
	v_fma_f32 v240, -v46, v6, v240
	v_fma_f32 v241, -v47, v7, v241
	ds_read_b128 v[4:7], v61 offset:58256
	s_waitcnt lgkmcnt(11)
	v_fma_f32 v205, -v48, v8, v205
	ds_read_b128 v[8:11], v61 offset:58272
	v_add_f32_e32 v13, v240, v241
	v_add_f32_e32 v12, v205, v219
	v_add_f32_e32 v49, v13, v12
	v_cvt_pk_bf16_f32 v15, v49, s0
	ds_write_b16 v110, v15 offset:38672
	s_waitcnt lgkmcnt(12)
	v_fma_f32 v205, -v111, v16, v142
	v_fma_f32 v219, -v21, v17, 0
	v_fma_f32 v240, -v22, v18, 0
	v_fma_f32 v241, -v23, v19, 0
	ds_read_b128 v[16:19], v61 offset:58288
	s_waitcnt lgkmcnt(12)
	v_fma_f32 v205, -v24, v206, v205
	v_fma_f32 v219, -v25, v207, v219
	v_fma_f32 v240, -v26, v208, v240
	v_fma_f32 v241, -v27, v209, v241
	ds_read_b128 v[206:209], v61 offset:58304
	s_waitcnt lgkmcnt(12)
	v_fma_f32 v205, -v28, v210, v205
	v_fma_f32 v219, -v29, v211, v219
	v_fma_f32 v240, -v30, v212, v240
	v_fma_f32 v241, -v31, v213, v241
	ds_read_b128 v[210:213], v61 offset:58320
	s_waitcnt lgkmcnt(11)
	v_fma_f32 v205, -v32, v214, v205
	v_fma_f32 v219, -v33, v215, v219
	v_fma_f32 v240, -v34, v216, v240
	v_fma_f32 v241, -v35, v217, v241
	ds_read_b128 v[214:217], v61 offset:58336
	s_waitcnt lgkmcnt(11)
	v_fma_f32 v205, -v36, v220, v205
	v_fma_f32 v219, -v37, v221, v219
	v_fma_f32 v240, -v38, v222, v240
	v_fma_f32 v241, -v39, v223, v241
	ds_read_b128 v[220:223], v61 offset:58352
	s_waitcnt lgkmcnt(11)
	v_fma_f32 v205, -v40, v224, v205
	v_fma_f32 v219, -v41, v225, v219
	v_fma_f32 v240, -v42, v226, v240
	v_fma_f32 v241, -v43, v227, v241
	s_waitcnt lgkmcnt(10)
	v_fma_f32 v205, -v44, v228, v205
	v_fma_f32 v219, -v45, v229, v219
	v_fma_f32 v240, -v46, v230, v240
	v_fma_f32 v241, -v47, v231, v241
	s_waitcnt lgkmcnt(9)
	v_fma_f32 v205, -v48, v232, v205
	v_fma_f32 v219, -v49, v233, v219
	v_add_f32_e32 v13, v240, v241
	v_add_f32_e32 v12, v205, v219
	v_add_f32_e32 v50, v13, v12
	v_cvt_pk_bf16_f32 v15, v50, s0
	ds_write_b16 v110, v15 offset:38752
	s_waitcnt lgkmcnt(9)
	v_fma_f32 v205, -v111, v236, v143
	v_fma_f32 v219, -v21, v237, 0
	v_fma_f32 v240, -v22, v238, 0
	v_fma_f32 v241, -v23, v239, 0
	s_waitcnt lgkmcnt(8)
	v_fma_f32 v205, -v24, v4, v205
	v_fma_f32 v219, -v25, v5, v219
	v_fma_f32 v240, -v26, v6, v240
	v_fma_f32 v241, -v27, v7, v241
	s_waitcnt lgkmcnt(7)
	v_fma_f32 v205, -v28, v8, v205
	v_fma_f32 v219, -v29, v9, v219
	v_fma_f32 v240, -v30, v10, v240
	v_fma_f32 v241, -v31, v11, v241
	s_waitcnt lgkmcnt(5)
	v_fma_f32 v205, -v32, v16, v205
	v_fma_f32 v219, -v33, v17, v219
	v_fma_f32 v240, -v34, v18, v240
	v_fma_f32 v241, -v35, v19, v241
	s_waitcnt lgkmcnt(4)
	v_fma_f32 v205, -v36, v206, v205
	v_fma_f32 v219, -v37, v207, v219
	v_fma_f32 v240, -v38, v208, v240
	v_fma_f32 v241, -v39, v209, v241
	s_waitcnt lgkmcnt(3)
	v_fma_f32 v205, -v40, v210, v205
	v_fma_f32 v219, -v41, v211, v219
	v_fma_f32 v240, -v42, v212, v240
	v_fma_f32 v241, -v43, v213, v241
	s_waitcnt lgkmcnt(2)
	v_fma_f32 v205, -v44, v214, v205
	v_fma_f32 v219, -v45, v215, v219
	v_fma_f32 v240, -v46, v216, v240
	v_fma_f32 v241, -v47, v217, v241
	s_waitcnt lgkmcnt(1)
	v_fma_f32 v205, -v48, v220, v205
	v_fma_f32 v219, -v49, v221, v219
	v_fma_f32 v240, -v50, v222, v240
	v_add_f32_e32 v12, v205, v219
	v_add_f32_e32 v13, v240, v241
	v_add_f32_e32 v20, v13, v12
	v_cvt_pk_bf16_f32 v15, v20, s0
	ds_write_b16 v110, v15 offset:38832
	s_branch .LBB0_492

.LBB0_695:
	s_or_b64 exec, exec, s[42:43]
	s_waitcnt lgkmcnt(0)
	s_barrier
	ds_read_b128 v[0:3], v109 offset:23552
	v_add_u32_e32 v14, v101, v104
	ds_read_b128 v[4:7], v14 offset:28672
	s_waitcnt lgkmcnt(0)
	v_mfma_f32_16x16x32_bf16 v[4:7], v[0:3], v[4:7], 0
	s_nop 7
	v_cvt_pk_bf16_f32 v4, v4, s0
	v_cvt_pk_bf16_f32 v5, v5, s0
	v_cvt_pk_bf16_f32 v6, v6, s0
	v_cvt_pk_bf16_f32 v7, v7, s0
	ds_write_b16 v163, v4 offset:38912
	ds_write_b16 v163, v5 offset:38992
	ds_write_b16 v164, v6 offset:38912
	ds_write_b16 v151, v7 offset:38912
	ds_read_b128 v[4:7], v14 offset:29952
	s_waitcnt lgkmcnt(0)
	v_mfma_f32_16x16x32_bf16 v[4:7], v[0:3], v[4:7], 0
	s_nop 7
	v_cvt_pk_bf16_f32 v4, v4, s0
	v_cvt_pk_bf16_f32 v5, v5, s0
	v_cvt_pk_bf16_f32 v6, v6, s0
	v_cvt_pk_bf16_f32 v7, v7, s0
	ds_write_b16 v163, v4 offset:38944
	ds_write_b16 v163, v5 offset:39024
	ds_write_b16 v164, v6 offset:38944
	ds_write_b16 v151, v7 offset:38944
	s_and_saveexec_b64 s[42:43], s[0:1]
	s_cbranch_execz .LBB0_641
	ds_read_b128 v[206:209], v61 offset:54400
	ds_read_b128 v[210:213], v61 offset:54528
	ds_read_b128 v[214:217], v61 offset:54656
	ds_read_b128 v[220:223], v61 offset:54784
	ds_read_b128 v[224:227], v61 offset:54912
	ds_read_b128 v[228:231], v61 offset:54928
	ds_read_b128 v[232:235], v61 offset:55040
	ds_read_b128 v[236:239], v61 offset:55056
	ds_read_b128 v[4:7], v61 offset:55168
	ds_read_b128 v[8:11], v61 offset:55184
	ds_read_b128 v[16:19], v61 offset:55296
	ds_write_b16 v110, v112 offset:36352
	s_waitcnt lgkmcnt(11)
	v_fma_f32 v21, -v111, v206, v113
	ds_read_b128 v[206:209], v61 offset:55312
	v_cvt_pk_bf16_f32 v15, v21, s0
	ds_write_b16 v110, v15 offset:36432
	s_waitcnt lgkmcnt(12)
	v_fma_f32 v205, -v111, v210, v114
	v_fma_f32 v219, -v21, v211, 0
	ds_read_b128 v[210:213], v61 offset:55424
	v_add_f32_e32 v22, v205, v219
	v_cvt_pk_bf16_f32 v15, v22, s0
	ds_write_b16 v110, v15 offset:36512
	s_waitcnt lgkmcnt(13)
	v_fma_f32 v205, -v111, v214, v115
	v_fma_f32 v219, -v21, v215, 0
	v_fma_f32 v240, -v22, v216, 0
	ds_read_b128 v[214:217], v61 offset:55440
	v_add_f32_e32 v12, v205, v219
	v_add_f32_e32 v23, v240, v12
	v_cvt_pk_bf16_f32 v15, v23, s0
	ds_write_b16 v110, v15 offset:36592
	s_waitcnt lgkmcnt(14)
	v_fma_f32 v205, -v111, v220, v116
	v_fma_f32 v219, -v21, v221, 0
	v_fma_f32 v240, -v22, v222, 0
	v_fma_f32 v241, -v23, v223, 0
	ds_read_b128 v[220:223], v61 offset:55456
	v_add_f32_e32 v12, v205, v219
	v_add_f32_e32 v13, v240, v241
	v_add_f32_e32 v24, v13, v12
	v_cvt_pk_bf16_f32 v15, v24, s0
	ds_write_b16 v110, v15 offset:36672
	s_waitcnt lgkmcnt(15)
	v_fma_f32 v205, -v111, v224, v117
	v_fma_f32 v219, -v21, v225, 0
	v_fma_f32 v240, -v22, v226, 0
	v_fma_f32 v241, -v23, v227, 0
	ds_read_b128 v[224:227], v61 offset:55552
	s_waitcnt lgkmcnt(15)
	v_fma_f32 v205, -v24, v228, v205
	ds_read_b128 v[228:231], v61 offset:55568
	v_add_f32_e32 v13, v240, v241
	v_add_f32_e32 v12, v205, v219
	v_add_f32_e32 v25, v13, v12
	v_cvt_pk_bf16_f32 v15, v25, s0
	ds_write_b16 v110, v15 offset:36752
	s_waitcnt lgkmcnt(15)
	v_fma_f32 v205, -v111, v232, v118
	v_fma_f32 v219, -v21, v233, 0
	v_fma_f32 v240, -v22, v234, 0
	v_fma_f32 v241, -v23, v235, 0
	ds_read_b128 v[232:235], v61 offset:55584
	s_waitcnt lgkmcnt(15)
	v_fma_f32 v205, -v24, v236, v205
	v_fma_f32 v219, -v25, v237, v219
	ds_read_b128 v[236:239], v61 offset:55680
	v_add_f32_e32 v13, v240, v241
	v_add_f32_e32 v12, v205, v219
	v_add_f32_e32 v26, v13, v12
	v_cvt_pk_bf16_f32 v15, v26, s0
	ds_write_b16 v110, v15 offset:36832
	s_waitcnt lgkmcnt(15)
	v_fma_f32 v205, -v111, v4, v119
	v_fma_f32 v219, -v21, v5, 0
	v_fma_f32 v240, -v22, v6, 0
	v_fma_f32 v241, -v23, v7, 0
	ds_read_b128 v[4:7], v61 offset:55696
	s_waitcnt lgkmcnt(15)
	v_fma_f32 v205, -v24, v8, v205
	v_fma_f32 v219, -v25, v9, v219
	v_fma_f32 v240, -v26, v10, v240
	ds_read_b128 v[8:11], v61 offset:55712
	v_add_f32_e32 v12, v205, v219
	v_add_f32_e32 v13, v240, v241
	v_add_f32_e32 v27, v13, v12
	v_cvt_pk_bf16_f32 v15, v27, s0
	ds_write_b16 v110, v15 offset:36912
	s_waitcnt lgkmcnt(15)
	v_fma_f32 v205, -v111, v16, v120
	v_fma_f32 v219, -v21, v17, 0
	v_fma_f32 v240, -v22, v18, 0
	v_fma_f32 v241, -v23, v19, 0
	ds_read_b128 v[16:19], v61 offset:55808
	s_waitcnt lgkmcnt(15)
	v_fma_f32 v205, -v24, v206, v205
	v_fma_f32 v219, -v25, v207, v219
	v_fma_f32 v240, -v26, v208, v240
	v_fma_f32 v241, -v27, v209, v241
	ds_read_b128 v[206:209], v61 offset:55824
	v_add_f32_e32 v12, v205, v219
	v_add_f32_e32 v13, v240, v241
	v_add_f32_e32 v28, v13, v12
	v_cvt_pk_bf16_f32 v15, v28, s0
	ds_write_b16 v110, v15 offset:36992
	s_waitcnt lgkmcnt(15)
	v_fma_f32 v205, -v111, v210, v121
	v_fma_f32 v219, -v21, v211, 0
	v_fma_f32 v240, -v22, v212, 0
	v_fma_f32 v241, -v23, v213, 0
	ds_read_b128 v[210:213], v61 offset:55840
	s_waitcnt lgkmcnt(15)
	v_fma_f32 v205, -v24, v214, v205
	v_fma_f32 v219, -v25, v215, v219
	v_fma_f32 v240, -v26, v216, v240
	v_fma_f32 v241, -v27, v217, v241
	ds_read_b128 v[214:217], v61 offset:55936
	s_waitcnt lgkmcnt(15)
	v_fma_f32 v205, -v28, v220, v205
	ds_read_b128 v[220:223], v61 offset:55952
	v_add_f32_e32 v13, v240, v241
	v_add_f32_e32 v12, v205, v219
	v_add_f32_e32 v29, v13, v12
	v_cvt_pk_bf16_f32 v15, v29, s0
	ds_write_b16 v110, v15 offset:37072
	s_waitcnt lgkmcnt(15)
	v_fma_f32 v205, -v111, v224, v122
	v_fma_f32 v219, -v21, v225, 0
	v_fma_f32 v240, -v22, v226, 0
	v_fma_f32 v241, -v23, v227, 0
	ds_read_b128 v[224:227], v61 offset:55968
	s_waitcnt lgkmcnt(15)
	v_fma_f32 v205, -v24, v228, v205
	v_fma_f32 v219, -v25, v229, v219
	v_fma_f32 v240, -v26, v230, v240
	v_fma_f32 v241, -v27, v231, v241
	ds_read_b128 v[228:231], v61 offset:55984
	s_waitcnt lgkmcnt(14)
	v_fma_f32 v205, -v28, v232, v205
	v_fma_f32 v219, -v29, v233, v219
	ds_read_b128 v[232:235], v61 offset:56064
	v_add_f32_e32 v13, v240, v241
	v_add_f32_e32 v12, v205, v219
	v_add_f32_e32 v30, v13, v12
	v_cvt_pk_bf16_f32 v15, v30, s0
	ds_write_b16 v110, v15 offset:37152
	s_waitcnt lgkmcnt(15)
	v_fma_f32 v205, -v111, v236, v123
	v_fma_f32 v219, -v21, v237, 0
	v_fma_f32 v240, -v22, v238, 0
	v_fma_f32 v241, -v23, v239, 0
	ds_read_b128 v[236:239], v61 offset:56080
	s_waitcnt lgkmcnt(14)
	v_fma_f32 v205, -v24, v4, v205
	v_fma_f32 v219, -v25, v5, v219
	v_fma_f32 v240, -v26, v6, v240
	v_fma_f32 v241, -v27, v7, v241
	ds_read_b128 v[4:7], v61 offset:56096
	s_waitcnt lgkmcnt(14)
	v_fma_f32 v205, -v28, v8, v205
	v_fma_f32 v219, -v29, v9, v219
	v_fma_f32 v240, -v30, v10, v240
	ds_read_b128 v[8:11], v61 offset:56112
	v_add_f32_e32 v12, v205, v219
	v_add_f32_e32 v13, v240, v241
	v_add_f32_e32 v31, v13, v12
	v_cvt_pk_bf16_f32 v15, v31, s0
	ds_write_b16 v110, v15 offset:37232
	s_waitcnt lgkmcnt(14)
	v_fma_f32 v205, -v111, v16, v124
	v_fma_f32 v219, -v21, v17, 0
	v_fma_f32 v240, -v22, v18, 0
	v_fma_f32 v241, -v23, v19, 0
	ds_read_b128 v[16:19], v61 offset:56192
	s_waitcnt lgkmcnt(14)
	v_fma_f32 v205, -v24, v206, v205
	v_fma_f32 v219, -v25, v207, v219
	v_fma_f32 v240, -v26, v208, v240
	v_fma_f32 v241, -v27, v209, v241
	ds_read_b128 v[206:209], v61 offset:56208
	s_waitcnt lgkmcnt(13)
	v_fma_f32 v205, -v28, v210, v205
	v_fma_f32 v219, -v29, v211, v219
	v_fma_f32 v240, -v30, v212, v240
	v_fma_f32 v241, -v31, v213, v241
	ds_read_b128 v[210:213], v61 offset:56224
	v_add_f32_e32 v12, v205, v219
	v_add_f32_e32 v13, v240, v241
	v_add_f32_e32 v32, v13, v12
	v_cvt_pk_bf16_f32 v15, v32, s0
	ds_write_b16 v110, v15 offset:37312
	s_waitcnt lgkmcnt(14)
	v_fma_f32 v205, -v111, v214, v125
	v_fma_f32 v219, -v21, v215, 0
	v_fma_f32 v240, -v22, v216, 0
	v_fma_f32 v241, -v23, v217, 0
	ds_read_b128 v[214:217], v61 offset:56240
	s_waitcnt lgkmcnt(14)
	v_fma_f32 v205, -v24, v220, v205
	v_fma_f32 v219, -v25, v221, v219
	v_fma_f32 v240, -v26, v222, v240
	v_fma_f32 v241, -v27, v223, v241
	ds_read_b128 v[220:223], v61 offset:56320
	s_waitcnt lgkmcnt(13)
	v_fma_f32 v205, -v28, v224, v205
	v_fma_f32 v219, -v29, v225, v219
	v_fma_f32 v240, -v30, v226, v240
	v_fma_f32 v241, -v31, v227, v241
	ds_read_b128 v[224:227], v61 offset:56336
	s_waitcnt lgkmcnt(13)
	v_fma_f32 v205, -v32, v228, v205
	ds_read_b128 v[228:231], v61 offset:56352
	v_add_f32_e32 v13, v240, v241
	v_add_f32_e32 v12, v205, v219
	v_add_f32_e32 v33, v13, v12
	v_cvt_pk_bf16_f32 v15, v33, s0
	ds_write_b16 v110, v15 offset:37392
	s_waitcnt lgkmcnt(14)
	v_fma_f32 v205, -v111, v232, v126
	v_fma_f32 v219, -v21, v233, 0
	v_fma_f32 v240, -v22, v234, 0
	v_fma_f32 v241, -v23, v235, 0
	ds_read_b128 v[232:235], v61 offset:56368
	s_waitcnt lgkmcnt(13)
	v_fma_f32 v205, -v24, v236, v205
	v_fma_f32 v219, -v25, v237, v219
	v_fma_f32 v240, -v26, v238, v240
	v_fma_f32 v241, -v27, v239, v241
	ds_read_b128 v[236:239], v61 offset:56448
	s_waitcnt lgkmcnt(13)
	v_fma_f32 v205, -v28, v4, v205
	v_fma_f32 v219, -v29, v5, v219
	v_fma_f32 v240, -v30, v6, v240
	v_fma_f32 v241, -v31, v7, v241
	ds_read_b128 v[4:7], v61 offset:56464
	s_waitcnt lgkmcnt(13)
	v_fma_f32 v205, -v32, v8, v205
	v_fma_f32 v219, -v33, v9, v219
	ds_read_b128 v[8:11], v61 offset:56480
	v_add_f32_e32 v13, v240, v241
	v_add_f32_e32 v12, v205, v219
	v_add_f32_e32 v34, v13, v12
	v_cvt_pk_bf16_f32 v15, v34, s0
	ds_write_b16 v110, v15 offset:37472
	s_waitcnt lgkmcnt(13)
	v_fma_f32 v205, -v111, v16, v127
	v_fma_f32 v219, -v21, v17, 0
	v_fma_f32 v240, -v22, v18, 0
	v_fma_f32 v241, -v23, v19, 0
	ds_read_b128 v[16:19], v61 offset:56496
	s_waitcnt lgkmcnt(13)
	v_fma_f32 v205, -v24, v206, v205
	v_fma_f32 v219, -v25, v207, v219
	v_fma_f32 v240, -v26, v208, v240
	v_fma_f32 v241, -v27, v209, v241
	ds_read_b128 v[206:209], v61 offset:56512
	s_waitcnt lgkmcnt(13)
	v_fma_f32 v205, -v28, v210, v205
	v_fma_f32 v219, -v29, v211, v219
	v_fma_f32 v240, -v30, v212, v240
	v_fma_f32 v241, -v31, v213, v241
	ds_read_b128 v[210:213], v61 offset:56576
	s_waitcnt lgkmcnt(12)
	v_fma_f32 v205, -v32, v214, v205
	v_fma_f32 v219, -v33, v215, v219
	v_fma_f32 v240, -v34, v216, v240
	ds_read_b128 v[214:217], v61 offset:56592
	v_add_f32_e32 v12, v205, v219
	v_add_f32_e32 v13, v240, v241
	v_add_f32_e32 v35, v13, v12
	v_cvt_pk_bf16_f32 v15, v35, s0
	ds_write_b16 v110, v15 offset:37552
	s_waitcnt lgkmcnt(13)
	v_fma_f32 v205, -v111, v220, v128
	v_fma_f32 v219, -v21, v221, 0
	v_fma_f32 v240, -v22, v222, 0
	v_fma_f32 v241, -v23, v223, 0
	ds_read_b128 v[220:223], v61 offset:56608
	s_waitcnt lgkmcnt(13)
	v_fma_f32 v205, -v24, v224, v205
	v_fma_f32 v219, -v25, v225, v219
	v_fma_f32 v240, -v26, v226, v240
	v_fma_f32 v241, -v27, v227, v241
	ds_read_b128 v[224:227], v61 offset:56624
	s_waitcnt lgkmcnt(13)
	v_fma_f32 v205, -v28, v228, v205
	v_fma_f32 v219, -v29, v229, v219
	v_fma_f32 v240, -v30, v230, v240
	v_fma_f32 v241, -v31, v231, v241
	ds_read_b128 v[228:231], v61 offset:56640
	s_waitcnt lgkmcnt(12)
	v_fma_f32 v205, -v32, v232, v205
	v_fma_f32 v219, -v33, v233, v219
	v_fma_f32 v240, -v34, v234, v240
	v_fma_f32 v241, -v35, v235, v241
	ds_read_b128 v[232:235], v61 offset:56704
	v_add_f32_e32 v12, v205, v219
	v_add_f32_e32 v13, v240, v241
	v_add_f32_e32 v36, v13, v12
	v_cvt_pk_bf16_f32 v15, v36, s0
	ds_write_b16 v110, v15 offset:37632
	s_waitcnt lgkmcnt(13)
	v_fma_f32 v205, -v111, v236, v129
	v_fma_f32 v219, -v21, v237, 0
	v_fma_f32 v240, -v22, v238, 0
	v_fma_f32 v241, -v23, v239, 0
	ds_read_b128 v[236:239], v61 offset:56720
	s_waitcnt lgkmcnt(13)
	v_fma_f32 v205, -v24, v4, v205
	v_fma_f32 v219, -v25, v5, v219
	v_fma_f32 v240, -v26, v6, v240
	v_fma_f32 v241, -v27, v7, v241
	ds_read_b128 v[4:7], v61 offset:56736
	s_waitcnt lgkmcnt(13)
	v_fma_f32 v205, -v28, v8, v205
	v_fma_f32 v219, -v29, v9, v219
	v_fma_f32 v240, -v30, v10, v240
	v_fma_f32 v241, -v31, v11, v241
	ds_read_b128 v[8:11], v61 offset:56752
	s_waitcnt lgkmcnt(12)
	v_fma_f32 v205, -v32, v16, v205
	v_fma_f32 v219, -v33, v17, v219
	v_fma_f32 v240, -v34, v18, v240
	v_fma_f32 v241, -v35, v19, v241
	ds_read_b128 v[16:19], v61 offset:56768
	s_waitcnt lgkmcnt(12)
	v_fma_f32 v205, -v36, v206, v205
	ds_read_b128 v[206:209], v61 offset:56832
	v_add_f32_e32 v13, v240, v241
	v_add_f32_e32 v12, v205, v219
	v_add_f32_e32 v37, v13, v12
	v_cvt_pk_bf16_f32 v15, v37, s0
	ds_write_b16 v110, v15 offset:37712
	s_waitcnt lgkmcnt(13)
	v_fma_f32 v205, -v111, v210, v130
	v_fma_f32 v219, -v21, v211, 0
	v_fma_f32 v240, -v22, v212, 0
	v_fma_f32 v241, -v23, v213, 0
	ds_read_b128 v[210:213], v61 offset:56848
	s_waitcnt lgkmcnt(13)
	v_fma_f32 v205, -v24, v214, v205
	v_fma_f32 v219, -v25, v215, v219
	v_fma_f32 v240, -v26, v216, v240
	v_fma_f32 v241, -v27, v217, v241
	ds_read_b128 v[214:217], v61 offset:56864
	s_waitcnt lgkmcnt(12)
	v_fma_f32 v205, -v28, v220, v205
	v_fma_f32 v219, -v29, v221, v219
	v_fma_f32 v240, -v30, v222, v240
	v_fma_f32 v241, -v31, v223, v241
	ds_read_b128 v[220:223], v61 offset:56880
	s_waitcnt lgkmcnt(12)
	v_fma_f32 v205, -v32, v224, v205
	v_fma_f32 v219, -v33, v225, v219
	v_fma_f32 v240, -v34, v226, v240
	v_fma_f32 v241, -v35, v227, v241
	ds_read_b128 v[224:227], v61 offset:56896
	s_waitcnt lgkmcnt(12)
	v_fma_f32 v205, -v36, v228, v205
	v_fma_f32 v219, -v37, v229, v219
	ds_read_b128 v[228:231], v61 offset:56960
	v_add_f32_e32 v13, v240, v241
	v_add_f32_e32 v12, v205, v219
	v_add_f32_e32 v38, v13, v12
	v_cvt_pk_bf16_f32 v15, v38, s0
	ds_write_b16 v110, v15 offset:37792
	s_waitcnt lgkmcnt(13)
	v_fma_f32 v205, -v111, v232, v131
	v_fma_f32 v219, -v21, v233, 0
	v_fma_f32 v240, -v22, v234, 0
	v_fma_f32 v241, -v23, v235, 0
	ds_read_b128 v[232:235], v61 offset:56976
	s_waitcnt lgkmcnt(12)
	v_fma_f32 v205, -v24, v236, v205
	v_fma_f32 v219, -v25, v237, v219
	v_fma_f32 v240, -v26, v238, v240
	v_fma_f32 v241, -v27, v239, v241
	ds_read_b128 v[236:239], v61 offset:56992
	s_waitcnt lgkmcnt(12)
	v_fma_f32 v205, -v28, v4, v205
	v_fma_f32 v219, -v29, v5, v219
	v_fma_f32 v240, -v30, v6, v240
	v_fma_f32 v241, -v31, v7, v241
	ds_read_b128 v[4:7], v61 offset:57008
	s_waitcnt lgkmcnt(12)
	v_fma_f32 v205, -v32, v8, v205
	v_fma_f32 v219, -v33, v9, v219
	v_fma_f32 v240, -v34, v10, v240
	v_fma_f32 v241, -v35, v11, v241
	ds_read_b128 v[8:11], v61 offset:57024
	s_waitcnt lgkmcnt(12)
	v_fma_f32 v205, -v36, v16, v205
	v_fma_f32 v219, -v37, v17, v219
	v_fma_f32 v240, -v38, v18, v240
	ds_read_b128 v[16:19], v61 offset:57040
	v_add_f32_e32 v12, v205, v219
	v_add_f32_e32 v13, v240, v241
	v_add_f32_e32 v39, v13, v12
	v_cvt_pk_bf16_f32 v15, v39, s0
	ds_write_b16 v110, v15 offset:37872
	s_waitcnt lgkmcnt(13)
	v_fma_f32 v205, -v111, v206, v132
	v_fma_f32 v219, -v21, v207, 0
	v_fma_f32 v240, -v22, v208, 0
	v_fma_f32 v241, -v23, v209, 0
	ds_read_b128 v[206:209], v61 offset:57088
	s_waitcnt lgkmcnt(12)
	v_fma_f32 v205, -v24, v210, v205
	v_fma_f32 v219, -v25, v211, v219
	v_fma_f32 v240, -v26, v212, v240
	v_fma_f32 v241, -v27, v213, v241
	ds_read_b128 v[210:213], v61 offset:57104
	s_waitcnt lgkmcnt(12)
	v_fma_f32 v205, -v28, v214, v205
	v_fma_f32 v219, -v29, v215, v219
	v_fma_f32 v240, -v30, v216, v240
	v_fma_f32 v241, -v31, v217, v241
	ds_read_b128 v[214:217], v61 offset:57120
	s_waitcnt lgkmcnt(12)
	v_fma_f32 v205, -v32, v220, v205
	v_fma_f32 v219, -v33, v221, v219
	v_fma_f32 v240, -v34, v222, v240
	v_fma_f32 v241, -v35, v223, v241
	ds_read_b128 v[220:223], v61 offset:57136
	s_waitcnt lgkmcnt(12)
	v_fma_f32 v205, -v36, v224, v205
	v_fma_f32 v219, -v37, v225, v219
	v_fma_f32 v240, -v38, v226, v240
	v_fma_f32 v241, -v39, v227, v241
	ds_read_b128 v[224:227], v61 offset:57152
	v_add_f32_e32 v12, v205, v219
	v_add_f32_e32 v13, v240, v241
	v_add_f32_e32 v40, v13, v12
	v_cvt_pk_bf16_f32 v15, v40, s0
	ds_write_b16 v110, v15 offset:37952
	s_waitcnt lgkmcnt(13)
	v_fma_f32 v205, -v111, v228, v133
	v_fma_f32 v219, -v21, v229, 0
	v_fma_f32 v240, -v22, v230, 0
	v_fma_f32 v241, -v23, v231, 0
	ds_read_b128 v[228:231], v61 offset:57168
	s_waitcnt lgkmcnt(12)
	v_fma_f32 v205, -v24, v232, v205
	v_fma_f32 v219, -v25, v233, v219
	v_fma_f32 v240, -v26, v234, v240
	v_fma_f32 v241, -v27, v235, v241
	ds_read_b128 v[232:235], v61 offset:57216
	s_waitcnt lgkmcnt(12)
	v_fma_f32 v205, -v28, v236, v205
	v_fma_f32 v219, -v29, v237, v219
	v_fma_f32 v240, -v30, v238, v240
	v_fma_f32 v241, -v31, v239, v241
	ds_read_b128 v[236:239], v61 offset:57232
	s_waitcnt lgkmcnt(12)
	v_fma_f32 v205, -v32, v4, v205
	v_fma_f32 v219, -v33, v5, v219
	v_fma_f32 v240, -v34, v6, v240
	v_fma_f32 v241, -v35, v7, v241
	ds_read_b128 v[4:7], v61 offset:57248
	s_waitcnt lgkmcnt(12)
	v_fma_f32 v205, -v36, v8, v205
	v_fma_f32 v219, -v37, v9, v219
	v_fma_f32 v240, -v38, v10, v240
	v_fma_f32 v241, -v39, v11, v241
	ds_read_b128 v[8:11], v61 offset:57264
	s_waitcnt lgkmcnt(12)
	v_fma_f32 v205, -v40, v16, v205
	ds_read_b128 v[16:19], v61 offset:57280
	v_add_f32_e32 v13, v240, v241
	v_add_f32_e32 v12, v205, v219
	v_add_f32_e32 v41, v13, v12
	v_cvt_pk_bf16_f32 v15, v41, s0
	ds_write_b16 v110, v15 offset:38032
	s_waitcnt lgkmcnt(12)
	v_fma_f32 v205, -v111, v206, v134
	v_fma_f32 v219, -v21, v207, 0
	v_fma_f32 v240, -v22, v208, 0
	v_fma_f32 v241, -v23, v209, 0
	ds_read_b128 v[206:209], v61 offset:57296
	s_waitcnt lgkmcnt(12)
	v_fma_f32 v205, -v24, v210, v205
	v_fma_f32 v219, -v25, v211, v219
	v_fma_f32 v240, -v26, v212, v240
	v_fma_f32 v241, -v27, v213, v241
	ds_read_b128 v[210:213], v61 offset:57344
	s_waitcnt lgkmcnt(12)
	v_fma_f32 v205, -v28, v214, v205
	v_fma_f32 v219, -v29, v215, v219
	v_fma_f32 v240, -v30, v216, v240
	v_fma_f32 v241, -v31, v217, v241
	ds_read_b128 v[214:217], v61 offset:57360
	s_waitcnt lgkmcnt(12)
	v_fma_f32 v205, -v32, v220, v205
	v_fma_f32 v219, -v33, v221, v219
	v_fma_f32 v240, -v34, v222, v240
	v_fma_f32 v241, -v35, v223, v241
	ds_read_b128 v[220:223], v61 offset:57376
	s_waitcnt lgkmcnt(12)
	v_fma_f32 v205, -v36, v224, v205
	v_fma_f32 v219, -v37, v225, v219
	v_fma_f32 v240, -v38, v226, v240
	v_fma_f32 v241, -v39, v227, v241
	ds_read_b128 v[224:227], v61 offset:57392
	s_waitcnt lgkmcnt(11)
	v_fma_f32 v205, -v40, v228, v205
	v_fma_f32 v219, -v41, v229, v219
	ds_read_b128 v[228:231], v61 offset:57408
	v_add_f32_e32 v13, v240, v241
	v_add_f32_e32 v12, v205, v219
	v_add_f32_e32 v42, v13, v12
	v_cvt_pk_bf16_f32 v15, v42, s0
	ds_write_b16 v110, v15 offset:38112
	s_waitcnt lgkmcnt(12)
	v_fma_f32 v205, -v111, v232, v135
	v_fma_f32 v219, -v21, v233, 0
	v_fma_f32 v240, -v22, v234, 0
	v_fma_f32 v241, -v23, v235, 0
	ds_read_b128 v[232:235], v61 offset:57424
	s_waitcnt lgkmcnt(12)
	v_fma_f32 v205, -v24, v236, v205
	v_fma_f32 v219, -v25, v237, v219
	v_fma_f32 v240, -v26, v238, v240
	v_fma_f32 v241, -v27, v239, v241
	ds_read_b128 v[236:239], v61 offset:57472
	s_waitcnt lgkmcnt(12)
	v_fma_f32 v205, -v28, v4, v205
	v_fma_f32 v219, -v29, v5, v219
	v_fma_f32 v240, -v30, v6, v240
	v_fma_f32 v241, -v31, v7, v241
	ds_read_b128 v[4:7], v61 offset:57488
	s_waitcnt lgkmcnt(12)
	v_fma_f32 v205, -v32, v8, v205
	v_fma_f32 v219, -v33, v9, v219
	v_fma_f32 v240, -v34, v10, v240
	v_fma_f32 v241, -v35, v11, v241
	ds_read_b128 v[8:11], v61 offset:57504
	s_waitcnt lgkmcnt(12)
	v_fma_f32 v205, -v36, v16, v205
	v_fma_f32 v219, -v37, v17, v219
	v_fma_f32 v240, -v38, v18, v240
	v_fma_f32 v241, -v39, v19, v241
	ds_read_b128 v[16:19], v61 offset:57520
	s_waitcnt lgkmcnt(11)
	v_fma_f32 v205, -v40, v206, v205
	v_fma_f32 v219, -v41, v207, v219
	v_fma_f32 v240, -v42, v208, v240
	ds_read_b128 v[206:209], v61 offset:57536
	v_add_f32_e32 v12, v205, v219
	v_add_f32_e32 v13, v240, v241
	v_add_f32_e32 v43, v13, v12
	v_cvt_pk_bf16_f32 v15, v43, s0
	ds_write_b16 v110, v15 offset:38192
	s_waitcnt lgkmcnt(12)
	v_fma_f32 v205, -v111, v210, v136
	v_fma_f32 v219, -v21, v211, 0
	v_fma_f32 v240, -v22, v212, 0
	v_fma_f32 v241, -v23, v213, 0
	ds_read_b128 v[210:213], v61 offset:57552
	s_waitcnt lgkmcnt(12)
	v_fma_f32 v205, -v24, v214, v205
	v_fma_f32 v219, -v25, v215, v219
	v_fma_f32 v240, -v26, v216, v240
	v_fma_f32 v241, -v27, v217, v241
	ds_read_b128 v[214:217], v61 offset:57568
	s_waitcnt lgkmcnt(12)
	v_fma_f32 v205, -v28, v220, v205
	v_fma_f32 v219, -v29, v221, v219
	v_fma_f32 v240, -v30, v222, v240
	v_fma_f32 v241, -v31, v223, v241
	ds_read_b128 v[220:223], v61 offset:57600
	s_waitcnt lgkmcnt(12)
	v_fma_f32 v205, -v32, v224, v205
	v_fma_f32 v219, -v33, v225, v219
	v_fma_f32 v240, -v34, v226, v240
	v_fma_f32 v241, -v35, v227, v241
	ds_read_b128 v[224:227], v61 offset:57616
	s_waitcnt lgkmcnt(12)
	v_fma_f32 v205, -v36, v228, v205
	v_fma_f32 v219, -v37, v229, v219
	v_fma_f32 v240, -v38, v230, v240
	v_fma_f32 v241, -v39, v231, v241
	ds_read_b128 v[228:231], v61 offset:57632
	s_waitcnt lgkmcnt(11)
	v_fma_f32 v205, -v40, v232, v205
	v_fma_f32 v219, -v41, v233, v219
	v_fma_f32 v240, -v42, v234, v240
	v_fma_f32 v241, -v43, v235, v241
	ds_read_b128 v[232:235], v61 offset:57648
	v_add_f32_e32 v12, v205, v219
	v_add_f32_e32 v13, v240, v241
	v_add_f32_e32 v44, v13, v12
	v_cvt_pk_bf16_f32 v15, v44, s0
	ds_write_b16 v110, v15 offset:38272
	s_waitcnt lgkmcnt(12)
	v_fma_f32 v205, -v111, v236, v137
	v_fma_f32 v219, -v21, v237, 0
	v_fma_f32 v240, -v22, v238, 0
	v_fma_f32 v241, -v23, v239, 0
	ds_read_b128 v[236:239], v61 offset:57664
	s_waitcnt lgkmcnt(12)
	v_fma_f32 v205, -v24, v4, v205
	v_fma_f32 v219, -v25, v5, v219
	v_fma_f32 v240, -v26, v6, v240
	v_fma_f32 v241, -v27, v7, v241
	ds_read_b128 v[4:7], v61 offset:57680
	s_waitcnt lgkmcnt(12)
	v_fma_f32 v205, -v28, v8, v205
	v_fma_f32 v219, -v29, v9, v219
	v_fma_f32 v240, -v30, v10, v240
	v_fma_f32 v241, -v31, v11, v241
	ds_read_b128 v[8:11], v61 offset:57696
	s_waitcnt lgkmcnt(12)
	v_fma_f32 v205, -v32, v16, v205
	v_fma_f32 v219, -v33, v17, v219
	v_fma_f32 v240, -v34, v18, v240
	v_fma_f32 v241, -v35, v19, v241
	ds_read_b128 v[16:19], v61 offset:57728
	s_waitcnt lgkmcnt(12)
	v_fma_f32 v205, -v36, v206, v205
	v_fma_f32 v219, -v37, v207, v219
	v_fma_f32 v240, -v38, v208, v240
	v_fma_f32 v241, -v39, v209, v241
	ds_read_b128 v[206:209], v61 offset:57744
	s_waitcnt lgkmcnt(11)
	v_fma_f32 v205, -v40, v210, v205
	v_fma_f32 v219, -v41, v211, v219
	v_fma_f32 v240, -v42, v212, v240
	v_fma_f32 v241, -v43, v213, v241
	ds_read_b128 v[210:213], v61 offset:57760
	s_waitcnt lgkmcnt(11)
	v_fma_f32 v205, -v44, v214, v205
	ds_read_b128 v[214:217], v61 offset:57776
	v_add_f32_e32 v13, v240, v241
	v_add_f32_e32 v12, v205, v219
	v_add_f32_e32 v45, v13, v12
	v_cvt_pk_bf16_f32 v15, v45, s0
	ds_write_b16 v110, v15 offset:38352
	s_waitcnt lgkmcnt(12)
	v_fma_f32 v205, -v111, v220, v138
	v_fma_f32 v219, -v21, v221, 0
	v_fma_f32 v240, -v22, v222, 0
	v_fma_f32 v241, -v23, v223, 0
	ds_read_b128 v[220:223], v61 offset:57792
	s_waitcnt lgkmcnt(12)
	v_fma_f32 v205, -v24, v224, v205
	v_fma_f32 v219, -v25, v225, v219
	v_fma_f32 v240, -v26, v226, v240
	v_fma_f32 v241, -v27, v227, v241
	ds_read_b128 v[224:227], v61 offset:57808
	s_waitcnt lgkmcnt(12)
	v_fma_f32 v205, -v28, v228, v205
	v_fma_f32 v219, -v29, v229, v219
	v_fma_f32 v240, -v30, v230, v240
	v_fma_f32 v241, -v31, v231, v241
	ds_read_b128 v[228:231], v61 offset:57824
	s_waitcnt lgkmcnt(12)
	v_fma_f32 v205, -v32, v232, v205
	v_fma_f32 v219, -v33, v233, v219
	v_fma_f32 v240, -v34, v234, v240
	v_fma_f32 v241, -v35, v235, v241
	ds_read_b128 v[232:235], v61 offset:57856
	s_waitcnt lgkmcnt(11)
	v_fma_f32 v205, -v36, v236, v205
	v_fma_f32 v219, -v37, v237, v219
	v_fma_f32 v240, -v38, v238, v240
	v_fma_f32 v241, -v39, v239, v241
	ds_read_b128 v[236:239], v61 offset:57872
	s_waitcnt lgkmcnt(11)
	v_fma_f32 v205, -v40, v4, v205
	v_fma_f32 v219, -v41, v5, v219
	v_fma_f32 v240, -v42, v6, v240
	v_fma_f32 v241, -v43, v7, v241
	ds_read_b128 v[4:7], v61 offset:57888
	s_waitcnt lgkmcnt(11)
	v_fma_f32 v205, -v44, v8, v205
	v_fma_f32 v219, -v45, v9, v219
	ds_read_b128 v[8:11], v61 offset:57904
	v_add_f32_e32 v13, v240, v241
	v_add_f32_e32 v12, v205, v219
	v_add_f32_e32 v46, v13, v12
	v_cvt_pk_bf16_f32 v15, v46, s0
	ds_write_b16 v110, v15 offset:38432
	s_waitcnt lgkmcnt(12)
	v_fma_f32 v205, -v111, v16, v139
	v_fma_f32 v219, -v21, v17, 0
	v_fma_f32 v240, -v22, v18, 0
	v_fma_f32 v241, -v23, v19, 0
	ds_read_b128 v[16:19], v61 offset:57920
	s_waitcnt lgkmcnt(12)
	v_fma_f32 v205, -v24, v206, v205
	v_fma_f32 v219, -v25, v207, v219
	v_fma_f32 v240, -v26, v208, v240
	v_fma_f32 v241, -v27, v209, v241
	ds_read_b128 v[206:209], v61 offset:57936
	s_waitcnt lgkmcnt(12)
	v_fma_f32 v205, -v28, v210, v205
	v_fma_f32 v219, -v29, v211, v219
	v_fma_f32 v240, -v30, v212, v240
	v_fma_f32 v241, -v31, v213, v241
	ds_read_b128 v[210:213], v61 offset:57952
	s_waitcnt lgkmcnt(12)
	v_fma_f32 v205, -v32, v214, v205
	v_fma_f32 v219, -v33, v215, v219
	v_fma_f32 v240, -v34, v216, v240
	v_fma_f32 v241, -v35, v217, v241
	ds_read_b128 v[214:217], v61 offset:57984
	s_waitcnt lgkmcnt(11)
	v_fma_f32 v205, -v36, v220, v205
	v_fma_f32 v219, -v37, v221, v219
	v_fma_f32 v240, -v38, v222, v240
	v_fma_f32 v241, -v39, v223, v241
	ds_read_b128 v[220:223], v61 offset:58000
	s_waitcnt lgkmcnt(11)
	v_fma_f32 v205, -v40, v224, v205
	v_fma_f32 v219, -v41, v225, v219
	v_fma_f32 v240, -v42, v226, v240
	v_fma_f32 v241, -v43, v227, v241
	ds_read_b128 v[224:227], v61 offset:58016
	s_waitcnt lgkmcnt(11)
	v_fma_f32 v205, -v44, v228, v205
	v_fma_f32 v219, -v45, v229, v219
	v_fma_f32 v240, -v46, v230, v240
	ds_read_b128 v[228:231], v61 offset:58032
	v_add_f32_e32 v12, v205, v219
	v_add_f32_e32 v13, v240, v241
	v_add_f32_e32 v47, v13, v12
	v_cvt_pk_bf16_f32 v15, v47, s0
	ds_write_b16 v110, v15 offset:38512
	s_waitcnt lgkmcnt(12)
	v_fma_f32 v205, -v111, v232, v140
	v_fma_f32 v219, -v21, v233, 0
	v_fma_f32 v240, -v22, v234, 0
	v_fma_f32 v241, -v23, v235, 0
	ds_read_b128 v[232:235], v61 offset:58048
	s_waitcnt lgkmcnt(12)
	v_fma_f32 v205, -v24, v236, v205
	v_fma_f32 v219, -v25, v237, v219
	v_fma_f32 v240, -v26, v238, v240
	v_fma_f32 v241, -v27, v239, v241
	ds_read_b128 v[236:239], v61 offset:58064
	s_waitcnt lgkmcnt(12)
	v_fma_f32 v205, -v28, v4, v205
	v_fma_f32 v219, -v29, v5, v219
	v_fma_f32 v240, -v30, v6, v240
	v_fma_f32 v241, -v31, v7, v241
	ds_read_b128 v[4:7], v61 offset:58080
	s_waitcnt lgkmcnt(12)
	v_fma_f32 v205, -v32, v8, v205
	v_fma_f32 v219, -v33, v9, v219
	v_fma_f32 v240, -v34, v10, v240
	v_fma_f32 v241, -v35, v11, v241
	ds_read_b128 v[8:11], v61 offset:58096
	s_waitcnt lgkmcnt(11)
	v_fma_f32 v205, -v36, v16, v205
	v_fma_f32 v219, -v37, v17, v219
	v_fma_f32 v240, -v38, v18, v240
	v_fma_f32 v241, -v39, v19, v241
	ds_read_b128 v[16:19], v61 offset:58112
	s_waitcnt lgkmcnt(11)
	v_fma_f32 v205, -v40, v206, v205
	v_fma_f32 v219, -v41, v207, v219
	v_fma_f32 v240, -v42, v208, v240
	v_fma_f32 v241, -v43, v209, v241
	ds_read_b128 v[206:209], v61 offset:58128
	s_waitcnt lgkmcnt(11)
	v_fma_f32 v205, -v44, v210, v205
	v_fma_f32 v219, -v45, v211, v219
	v_fma_f32 v240, -v46, v212, v240
	v_fma_f32 v241, -v47, v213, v241
	ds_read_b128 v[210:213], v61 offset:58144
	v_add_f32_e32 v12, v205, v219
	v_add_f32_e32 v13, v240, v241
	v_add_f32_e32 v48, v13, v12
	v_cvt_pk_bf16_f32 v15, v48, s0
	ds_write_b16 v110, v15 offset:38592
	s_waitcnt lgkmcnt(12)
	v_fma_f32 v205, -v111, v214, v141
	v_fma_f32 v219, -v21, v215, 0
	v_fma_f32 v240, -v22, v216, 0
	v_fma_f32 v241, -v23, v217, 0
	ds_read_b128 v[214:217], v61 offset:58160
	s_waitcnt lgkmcnt(12)
	v_fma_f32 v205, -v24, v220, v205
	v_fma_f32 v219, -v25, v221, v219
	v_fma_f32 v240, -v26, v222, v240
	v_fma_f32 v241, -v27, v223, v241
	ds_read_b128 v[220:223], v61 offset:58176
	s_waitcnt lgkmcnt(12)
	v_fma_f32 v205, -v28, v224, v205
	v_fma_f32 v219, -v29, v225, v219
	v_fma_f32 v240, -v30, v226, v240
	v_fma_f32 v241, -v31, v227, v241
	ds_read_b128 v[224:227], v61 offset:58192
	s_waitcnt lgkmcnt(12)
	v_fma_f32 v205, -v32, v228, v205
	v_fma_f32 v219, -v33, v229, v219
	v_fma_f32 v240, -v34, v230, v240
	v_fma_f32 v241, -v35, v231, v241
	ds_read_b128 v[228:231], v61 offset:58208
	s_waitcnt lgkmcnt(11)
	v_fma_f32 v205, -v36, v232, v205
	v_fma_f32 v219, -v37, v233, v219
	v_fma_f32 v240, -v38, v234, v240
	v_fma_f32 v241, -v39, v235, v241
	ds_read_b128 v[232:235], v61 offset:58224
	s_waitcnt lgkmcnt(11)
	v_fma_f32 v205, -v40, v236, v205
	v_fma_f32 v219, -v41, v237, v219
	v_fma_f32 v240, -v42, v238, v240
	v_fma_f32 v241, -v43, v239, v241
	ds_read_b128 v[236:239], v61 offset:58240
	s_waitcnt lgkmcnt(11)
	v_fma_f32 v205, -v44, v4, v205
	v_fma_f32 v219, -v45, v5, v219
	v_fma_f32 v240, -v46, v6, v240
	v_fma_f32 v241, -v47, v7, v241
	ds_read_b128 v[4:7], v61 offset:58256
	s_waitcnt lgkmcnt(11)
	v_fma_f32 v205, -v48, v8, v205
	ds_read_b128 v[8:11], v61 offset:58272
	v_add_f32_e32 v13, v240, v241
	v_add_f32_e32 v12, v205, v219
	v_add_f32_e32 v49, v13, v12
	v_cvt_pk_bf16_f32 v15, v49, s0
	ds_write_b16 v110, v15 offset:38672
	s_waitcnt lgkmcnt(12)
	v_fma_f32 v205, -v111, v16, v142
	v_fma_f32 v219, -v21, v17, 0
	v_fma_f32 v240, -v22, v18, 0
	v_fma_f32 v241, -v23, v19, 0
	ds_read_b128 v[16:19], v61 offset:58288
	s_waitcnt lgkmcnt(12)
	v_fma_f32 v205, -v24, v206, v205
	v_fma_f32 v219, -v25, v207, v219
	v_fma_f32 v240, -v26, v208, v240
	v_fma_f32 v241, -v27, v209, v241
	ds_read_b128 v[206:209], v61 offset:58304
	s_waitcnt lgkmcnt(12)
	v_fma_f32 v205, -v28, v210, v205
	v_fma_f32 v219, -v29, v211, v219
	v_fma_f32 v240, -v30, v212, v240
	v_fma_f32 v241, -v31, v213, v241
	ds_read_b128 v[210:213], v61 offset:58320
	s_waitcnt lgkmcnt(11)
	v_fma_f32 v205, -v32, v214, v205
	v_fma_f32 v219, -v33, v215, v219
	v_fma_f32 v240, -v34, v216, v240
	v_fma_f32 v241, -v35, v217, v241
	ds_read_b128 v[214:217], v61 offset:58336
	s_waitcnt lgkmcnt(11)
	v_fma_f32 v205, -v36, v220, v205
	v_fma_f32 v219, -v37, v221, v219
	v_fma_f32 v240, -v38, v222, v240
	v_fma_f32 v241, -v39, v223, v241
	ds_read_b128 v[220:223], v61 offset:58352
	s_waitcnt lgkmcnt(11)
	v_fma_f32 v205, -v40, v224, v205
	v_fma_f32 v219, -v41, v225, v219
	v_fma_f32 v240, -v42, v226, v240
	v_fma_f32 v241, -v43, v227, v241
	s_waitcnt lgkmcnt(10)
	v_fma_f32 v205, -v44, v228, v205
	v_fma_f32 v219, -v45, v229, v219
	v_fma_f32 v240, -v46, v230, v240
	v_fma_f32 v241, -v47, v231, v241
	s_waitcnt lgkmcnt(9)
	v_fma_f32 v205, -v48, v232, v205
	v_fma_f32 v219, -v49, v233, v219
	v_add_f32_e32 v13, v240, v241
	v_add_f32_e32 v12, v205, v219
	v_add_f32_e32 v50, v13, v12
	v_cvt_pk_bf16_f32 v15, v50, s0
	ds_write_b16 v110, v15 offset:38752
	s_waitcnt lgkmcnt(9)
	v_fma_f32 v205, -v111, v236, v143
	v_fma_f32 v219, -v21, v237, 0
	v_fma_f32 v240, -v22, v238, 0
	v_fma_f32 v241, -v23, v239, 0
	s_waitcnt lgkmcnt(8)
	v_fma_f32 v205, -v24, v4, v205
	v_fma_f32 v219, -v25, v5, v219
	v_fma_f32 v240, -v26, v6, v240
	v_fma_f32 v241, -v27, v7, v241
	s_waitcnt lgkmcnt(7)
	v_fma_f32 v205, -v28, v8, v205
	v_fma_f32 v219, -v29, v9, v219
	v_fma_f32 v240, -v30, v10, v240
	v_fma_f32 v241, -v31, v11, v241
	s_waitcnt lgkmcnt(5)
	v_fma_f32 v205, -v32, v16, v205
	v_fma_f32 v219, -v33, v17, v219
	v_fma_f32 v240, -v34, v18, v240
	v_fma_f32 v241, -v35, v19, v241
	s_waitcnt lgkmcnt(4)
	v_fma_f32 v205, -v36, v206, v205
	v_fma_f32 v219, -v37, v207, v219
	v_fma_f32 v240, -v38, v208, v240
	v_fma_f32 v241, -v39, v209, v241
	s_waitcnt lgkmcnt(3)
	v_fma_f32 v205, -v40, v210, v205
	v_fma_f32 v219, -v41, v211, v219
	v_fma_f32 v240, -v42, v212, v240
	v_fma_f32 v241, -v43, v213, v241
	s_waitcnt lgkmcnt(2)
	v_fma_f32 v205, -v44, v214, v205
	v_fma_f32 v219, -v45, v215, v219
	v_fma_f32 v240, -v46, v216, v240
	v_fma_f32 v241, -v47, v217, v241
	s_waitcnt lgkmcnt(1)
	v_fma_f32 v205, -v48, v220, v205
	v_fma_f32 v219, -v49, v221, v219
	v_fma_f32 v240, -v50, v222, v240
	v_add_f32_e32 v12, v205, v219
	v_add_f32_e32 v13, v240, v241
	v_add_f32_e32 v20, v13, v12
	v_cvt_pk_bf16_f32 v15, v20, s0
	ds_write_b16 v110, v15 offset:38832
	s_branch .LBB0_641
